# v63 + input-projection epilogue: rotary-table loads of row-groups 2..8 issued at the start of their row-group into spare VGPRs (round trip overlaps the norm work)
# baseline (speedup 1.0000x reference)
.LBB0_493:
	v_mul_u32_u24_e32 v0, 0x700, v187
	s_lshl_b32 s88, s78, 6
	v_lshlrev_b32_e32 v0, 1, v0
	s_ashr_i32 s89, s88, 31
	v_lshl_add_u64 v[122:123], s[64:65], 0, v[0:1]
	v_lshl_add_u64 v[122:123], s[88:89], 1, v[122:123]
	v_add_u32_e32 v130, 16, v176
	v_add_u32_e32 v226, 16, v186
	v_and_b32_e32 v227, 63, v226
	v_bfe_u32 v224, v130, 6, 5
	v_and_b32_e32 v228, 0x7ff, v130
	v_cndmask_b32_e64 v224, v227, v224, s[44:45]
	v_cndmask_b32_e64 v228, v224, v228, s[42:43]
	v_lshlrev_b32_e32 v228, 7, v228
	v_mov_b32_e32 v229, v1
	v_lshl_add_u64 v[224:225], s[36:37], 0, v[228:229]
	v_mov_b32_e32 v230, v142
	v_mov_b32_e32 v231, v1
	v_lshl_add_u64 v[224:225], v[224:225], 0, v[230:231]
	global_load_dwordx4 v[208:211], v[224:225], off offset:48
	global_load_dwordx4 v[212:215], v[224:225], off offset:32
	global_load_dwordx4 v[216:219], v[224:225], off offset:16
	global_load_dwordx4 v[220:223], v[224:225], off
	v_lshl_add_u64 v[126:127], v[158:159], 1, v[122:123]
	v_cvt_pk_bf16_f32 v122, v134, v135
	v_cvt_pk_bf16_f32 v123, v136, v137
	v_cvt_pk_bf16_f32 v124, v118, v119
	v_cvt_pk_bf16_f32 v125, v120, v121
	v_cvt_pk_bf16_f32 v118, v138, v139
	v_cvt_pk_bf16_f32 v119, v140, v141
	v_cvt_pk_bf16_f32 v120, v114, v115
	v_cvt_pk_bf16_f32 v121, v116, v117
	v_and_b32_e32 v132, 0xff, v130
	global_store_dwordx4 v[126:127], v[122:125], off
	global_store_dwordx4 v[126:127], v[118:121], off offset:32
	v_lshl_add_u32 v0, v132, 2, 0
	v_add_u32_e32 v0, 0x20400, v0
	ds_read_b32 v0, v0
	s_cmp_lt_i32 s78, 20
	s_cbranch_scc1 .LBB0_496
	s_mov_b64 s[94:95], -1
	s_mov_b64 s[84:85], 0
	s_cmp_gt_i32 s78, 25
	s_mov_b64 s[86:87], 0
	s_cbranch_scc0 .LBB0_497
	s_cmp_eq_u32 s78, 26
	s_mov_b64 s[94:95], 0
	s_cselect_b64 s[86:87], -1, 0
	s_branch .LBB0_497

.LBB0_510:
	v_add_u32_e32 v0, 16, v186
	v_and_b32_e32 v126, 63, v0
	s_and_b64 vcc, exec, s[86:87]
	s_cbranch_vccz .LBB0_512
	v_mov_b32_e32 v143, v1
	v_mov_b32_e32 v110, v118
	v_mov_b32_e32 v111, v122
	s_waitcnt vmcnt(0)
	v_mov_b64_e32 v[114:115], v[208:209]
	v_mov_b64_e32 v[116:117], v[210:211]
	v_mov_b64_e32 v[128:129], v[212:213]
	v_mov_b64_e32 v[130:131], v[214:215]
	v_mov_b64_e32 v[134:135], v[216:217]
	v_mov_b64_e32 v[136:137], v[218:219]
	v_mov_b64_e32 v[106:107], v[220:221]
	v_mov_b64_e32 v[108:109], v[222:223]
	v_pk_mul_f32 v[110:111], v[110:111], v[106:107]
	s_nop 0
	v_sub_f32_e32 v0, v110, v111
	v_mov_b32_e32 v110, v122
	v_mov_b32_e32 v111, v118
	v_pk_mul_f32 v[106:107], v[110:111], v[106:107]
	s_nop 0
	v_add_f32_e32 v107, v107, v106
	v_cndmask_b32_e64 v106, v118, v0, s[40:41]
	v_cndmask_b32_e64 v110, v122, v107, s[40:41]
	v_mov_b32_e32 v122, v119
	v_mov_b32_e32 v118, v123
	v_pk_mul_f32 v[112:113], v[122:123], v[108:109]
	v_pk_mul_f32 v[108:109], v[118:119], v[108:109]
	v_sub_f32_e32 v0, v112, v113
	v_add_f32_e32 v108, v109, v108
	v_cndmask_b32_e64 v111, v123, v108, s[40:41]
	v_mov_b32_e32 v108, v120
	v_mov_b32_e32 v109, v124
	v_pk_mul_f32 v[108:109], v[108:109], v[134:135]
	v_cndmask_b32_e64 v107, v119, v0, s[40:41]
	v_sub_f32_e32 v0, v108, v109
	v_mov_b32_e32 v108, v124
	v_mov_b32_e32 v109, v120
	v_pk_mul_f32 v[108:109], v[108:109], v[134:135]
	s_nop 0
	v_add_f32_e32 v109, v109, v108
	v_cndmask_b32_e64 v112, v124, v109, s[40:41]
	v_mov_b32_e32 v124, v121
	v_cndmask_b32_e64 v108, v120, v0, s[40:41]
	v_pk_mul_f32 v[118:119], v[124:125], v[136:137]
	v_mov_b32_e32 v120, v125
	v_sub_f32_e32 v0, v118, v119
	v_pk_mul_f32 v[118:119], v[120:121], v[136:137]
	v_cndmask_b32_e64 v109, v121, v0, s[40:41]
	v_add_f32_e32 v113, v119, v118
	v_mov_b32_e32 v118, v102
	v_mov_b32_e32 v119, v98
	v_pk_mul_f32 v[118:119], v[118:119], v[128:129]
	v_cndmask_b32_e64 v113, v125, v113, s[40:41]
	v_sub_f32_e32 v0, v118, v119
	v_mov_b32_e32 v118, v98
	v_mov_b32_e32 v119, v102
	v_pk_mul_f32 v[118:119], v[118:119], v[128:129]
	s_nop 0
	v_add_f32_e32 v119, v119, v118
	v_cndmask_b32_e64 v122, v98, v119, s[40:41]
	v_mov_b32_e32 v98, v103
	v_cndmask_b32_e64 v118, v102, v0, s[40:41]
	v_pk_mul_f32 v[120:121], v[98:99], v[130:131]
	v_mov_b32_e32 v102, v99
	v_sub_f32_e32 v0, v120, v121
	v_pk_mul_f32 v[120:121], v[102:103], v[130:131]
	v_cndmask_b32_e64 v119, v103, v0, s[40:41]
	v_add_f32_e32 v98, v121, v120
	v_cndmask_b32_e64 v123, v99, v98, s[40:41]
	v_mov_b32_e32 v98, v104
	v_mov_b32_e32 v99, v100
	v_pk_mul_f32 v[98:99], v[98:99], v[114:115]
	s_nop 0
	v_sub_f32_e32 v0, v98, v99
	v_mov_b32_e32 v98, v100
	v_mov_b32_e32 v99, v104
	v_pk_mul_f32 v[98:99], v[98:99], v[114:115]
	v_cndmask_b32_e64 v120, v104, v0, s[40:41]
	v_add_f32_e32 v98, v99, v98
	v_cndmask_b32_e64 v124, v100, v98, s[40:41]
	v_mov_b32_e32 v100, v105
	v_pk_mul_f32 v[98:99], v[100:101], v[116:117]
	v_mov_b32_e32 v104, v101
	v_sub_f32_e32 v0, v98, v99
	v_pk_mul_f32 v[98:99], v[104:105], v[116:117]
	v_cndmask_b32_e64 v121, v105, v0, s[40:41]
	v_add_f32_e32 v98, v99, v98
	v_cndmask_b32_e64 v125, v101, v98, s[40:41]
	v_mov_b64_e32 v[98:99], v[122:123]
	v_mov_b64_e32 v[102:103], v[118:119]
	v_mov_b64_e32 v[100:101], v[124:125]
	v_mov_b64_e32 v[104:105], v[120:121]
	v_mov_b64_e32 v[124:125], v[112:113]
	v_mov_b64_e32 v[120:121], v[108:109]
	v_mov_b64_e32 v[122:123], v[110:111]
	v_mov_b64_e32 v[118:119], v[106:107]
.LBB0_512:
	v_mul_u32_u24_e32 v0, 0x700, v132
	v_lshlrev_b32_e32 v0, 1, v0
	v_lshl_add_u64 v[106:107], s[64:65], 0, v[0:1]
	v_lshl_add_u64 v[106:107], s[88:89], 1, v[106:107]
	v_add_u32_e32 v114, 32, v176
	v_add_u32_e32 v226, 32, v186
	v_and_b32_e32 v227, 63, v226
	v_bfe_u32 v224, v114, 6, 5
	v_and_b32_e32 v228, 0x7ff, v114
	v_cndmask_b32_e64 v224, v227, v224, s[44:45]
	v_cndmask_b32_e64 v228, v224, v228, s[42:43]
	v_lshlrev_b32_e32 v228, 7, v228
	v_mov_b32_e32 v229, v1
	v_lshl_add_u64 v[224:225], s[36:37], 0, v[228:229]
	v_mov_b32_e32 v230, v142
	v_mov_b32_e32 v231, v1
	v_lshl_add_u64 v[224:225], v[224:225], 0, v[230:231]
	global_load_dwordx4 v[208:211], v[224:225], off offset:48
	global_load_dwordx4 v[212:215], v[224:225], off offset:32
	global_load_dwordx4 v[216:219], v[224:225], off offset:16
	global_load_dwordx4 v[220:223], v[224:225], off
	v_lshl_add_u64 v[110:111], v[158:159], 1, v[106:107]
	v_cvt_pk_bf16_f32 v106, v118, v119
	v_cvt_pk_bf16_f32 v107, v120, v121
	v_cvt_pk_bf16_f32 v108, v102, v103
	v_cvt_pk_bf16_f32 v109, v104, v105
	v_cvt_pk_bf16_f32 v102, v122, v123
	v_cvt_pk_bf16_f32 v103, v124, v125
	v_cvt_pk_bf16_f32 v104, v98, v99
	v_cvt_pk_bf16_f32 v105, v100, v101
	v_and_b32_e32 v116, 0xff, v114
	global_store_dwordx4 v[110:111], v[106:109], off
	global_store_dwordx4 v[110:111], v[102:105], off offset:32
	v_lshl_add_u32 v0, v116, 2, 0
	v_add_u32_e32 v0, 0x20400, v0
	ds_read_b32 v0, v0
	s_cmp_lt_i32 s78, 20
	s_cbranch_scc1 .LBB0_515
	s_mov_b64 s[94:95], -1
	s_mov_b64 s[84:85], 0
	s_cmp_gt_i32 s78, 25
	s_mov_b64 s[86:87], 0
	s_cbranch_scc0 .LBB0_516
	s_cmp_eq_u32 s78, 26
	s_mov_b64 s[94:95], 0
	s_cselect_b64 s[86:87], -1, 0
	s_branch .LBB0_516

.LBB0_529:
	v_xor_b32_e32 v110, 32, v144
	s_and_b64 vcc, exec, s[86:87]
	s_cbranch_vccz .LBB0_531
	v_mov_b32_e32 v143, v1
	v_mov_b32_e32 v94, v102
	v_mov_b32_e32 v95, v106
	s_waitcnt vmcnt(0)
	v_mov_b64_e32 v[98:99], v[208:209]
	v_mov_b64_e32 v[100:101], v[210:211]
	v_mov_b64_e32 v[112:113], v[212:213]
	v_mov_b64_e32 v[114:115], v[214:215]
	v_mov_b64_e32 v[118:119], v[216:217]
	v_mov_b64_e32 v[120:121], v[218:219]
	v_mov_b64_e32 v[90:91], v[220:221]
	v_mov_b64_e32 v[92:93], v[222:223]
	v_pk_mul_f32 v[94:95], v[94:95], v[90:91]
	s_nop 0
	v_sub_f32_e32 v0, v94, v95
	v_mov_b32_e32 v94, v106
	v_mov_b32_e32 v95, v102
	v_pk_mul_f32 v[90:91], v[94:95], v[90:91]
	s_nop 0
	v_add_f32_e32 v91, v91, v90
	v_cndmask_b32_e64 v90, v102, v0, s[40:41]
	v_cndmask_b32_e64 v94, v106, v91, s[40:41]
	v_mov_b32_e32 v106, v103
	v_mov_b32_e32 v102, v107
	v_pk_mul_f32 v[96:97], v[106:107], v[92:93]
	v_pk_mul_f32 v[92:93], v[102:103], v[92:93]
	v_sub_f32_e32 v0, v96, v97
	v_add_f32_e32 v92, v93, v92
	v_cndmask_b32_e64 v95, v107, v92, s[40:41]
	v_mov_b32_e32 v92, v104
	v_mov_b32_e32 v93, v108
	v_pk_mul_f32 v[92:93], v[92:93], v[118:119]
	v_cndmask_b32_e64 v91, v103, v0, s[40:41]
	v_sub_f32_e32 v0, v92, v93
	v_mov_b32_e32 v92, v108
	v_mov_b32_e32 v93, v104
	v_pk_mul_f32 v[92:93], v[92:93], v[118:119]
	s_nop 0
	v_add_f32_e32 v93, v93, v92
	v_cndmask_b32_e64 v96, v108, v93, s[40:41]
	v_mov_b32_e32 v108, v105
	v_cndmask_b32_e64 v92, v104, v0, s[40:41]
	v_pk_mul_f32 v[102:103], v[108:109], v[120:121]
	v_mov_b32_e32 v104, v109
	v_sub_f32_e32 v0, v102, v103
	v_pk_mul_f32 v[102:103], v[104:105], v[120:121]
	v_cndmask_b32_e64 v93, v105, v0, s[40:41]
	v_add_f32_e32 v97, v103, v102
	v_mov_b32_e32 v102, v86
	v_mov_b32_e32 v103, v82
	v_pk_mul_f32 v[102:103], v[102:103], v[112:113]
	v_cndmask_b32_e64 v97, v109, v97, s[40:41]
	v_sub_f32_e32 v0, v102, v103
	v_mov_b32_e32 v102, v82
	v_mov_b32_e32 v103, v86
	v_pk_mul_f32 v[102:103], v[102:103], v[112:113]
	s_nop 0
	v_add_f32_e32 v103, v103, v102
	v_cndmask_b32_e64 v106, v82, v103, s[40:41]
	v_mov_b32_e32 v82, v87
	v_cndmask_b32_e64 v102, v86, v0, s[40:41]
	v_pk_mul_f32 v[104:105], v[82:83], v[114:115]
	v_mov_b32_e32 v86, v83
	v_sub_f32_e32 v0, v104, v105
	v_pk_mul_f32 v[104:105], v[86:87], v[114:115]
	v_cndmask_b32_e64 v103, v87, v0, s[40:41]
	v_add_f32_e32 v82, v105, v104
	v_cndmask_b32_e64 v107, v83, v82, s[40:41]
	v_mov_b32_e32 v82, v88
	v_mov_b32_e32 v83, v84
	v_pk_mul_f32 v[82:83], v[82:83], v[98:99]
	s_nop 0
	v_sub_f32_e32 v0, v82, v83
	v_mov_b32_e32 v82, v84
	v_mov_b32_e32 v83, v88
	v_pk_mul_f32 v[82:83], v[82:83], v[98:99]
	v_cndmask_b32_e64 v104, v88, v0, s[40:41]
	v_add_f32_e32 v82, v83, v82
	v_cndmask_b32_e64 v108, v84, v82, s[40:41]
	v_mov_b32_e32 v84, v89
	v_pk_mul_f32 v[82:83], v[84:85], v[100:101]
	v_mov_b32_e32 v88, v85
	v_sub_f32_e32 v0, v82, v83
	v_pk_mul_f32 v[82:83], v[88:89], v[100:101]
	v_cndmask_b32_e64 v105, v89, v0, s[40:41]
	v_add_f32_e32 v82, v83, v82
	v_cndmask_b32_e64 v109, v85, v82, s[40:41]
	v_mov_b64_e32 v[82:83], v[106:107]
	v_mov_b64_e32 v[86:87], v[102:103]
	v_mov_b64_e32 v[84:85], v[108:109]
	v_mov_b64_e32 v[88:89], v[104:105]
	v_mov_b64_e32 v[108:109], v[96:97]
	v_mov_b64_e32 v[104:105], v[92:93]
	v_mov_b64_e32 v[106:107], v[94:95]
	v_mov_b64_e32 v[102:103], v[90:91]
.LBB0_531:
	v_mul_u32_u24_e32 v0, 0x700, v116
	v_lshlrev_b32_e32 v0, 1, v0
	v_lshl_add_u64 v[90:91], s[64:65], 0, v[0:1]
	v_lshl_add_u64 v[90:91], s[88:89], 1, v[90:91]
	v_add_u32_e32 v98, 48, v176
	v_add_u32_e32 v226, 48, v186
	v_and_b32_e32 v227, 63, v226
	v_bfe_u32 v224, v98, 6, 5
	v_and_b32_e32 v228, 0x7ff, v98
	v_cndmask_b32_e64 v224, v227, v224, s[44:45]
	v_cndmask_b32_e64 v228, v224, v228, s[42:43]
	v_lshlrev_b32_e32 v228, 7, v228
	v_mov_b32_e32 v229, v1
	v_lshl_add_u64 v[224:225], s[36:37], 0, v[228:229]
	v_mov_b32_e32 v230, v142
	v_mov_b32_e32 v231, v1
	v_lshl_add_u64 v[224:225], v[224:225], 0, v[230:231]
	global_load_dwordx4 v[208:211], v[224:225], off offset:48
	global_load_dwordx4 v[212:215], v[224:225], off offset:32
	global_load_dwordx4 v[216:219], v[224:225], off offset:16
	global_load_dwordx4 v[220:223], v[224:225], off
	v_lshl_add_u64 v[94:95], v[158:159], 1, v[90:91]
	v_cvt_pk_bf16_f32 v90, v102, v103
	v_cvt_pk_bf16_f32 v91, v104, v105
	v_cvt_pk_bf16_f32 v92, v86, v87
	v_cvt_pk_bf16_f32 v93, v88, v89
	v_cvt_pk_bf16_f32 v86, v106, v107
	v_cvt_pk_bf16_f32 v87, v108, v109
	v_cvt_pk_bf16_f32 v88, v82, v83
	v_cvt_pk_bf16_f32 v89, v84, v85
	v_and_b32_e32 v100, 0xff, v98
	global_store_dwordx4 v[94:95], v[90:93], off
	global_store_dwordx4 v[94:95], v[86:89], off offset:32
	v_lshl_add_u32 v0, v100, 2, 0
	v_add_u32_e32 v0, 0x20400, v0
	ds_read_b32 v0, v0
	s_cmp_lt_i32 s78, 20
	s_cbranch_scc1 .LBB0_534
	s_mov_b64 s[94:95], -1
	s_mov_b64 s[84:85], 0
	s_cmp_gt_i32 s78, 25
	s_mov_b64 s[86:87], 0
	s_cbranch_scc0 .LBB0_535
	s_cmp_eq_u32 s78, 26
	s_mov_b64 s[94:95], 0
	s_cselect_b64 s[86:87], -1, 0
	s_branch .LBB0_535

.LBB0_548:
	v_add_u32_e32 v0, 48, v186
	v_and_b32_e32 v94, 63, v0
	s_and_b64 vcc, exec, s[86:87]
	s_cbranch_vccz .LBB0_550
	v_mov_b32_e32 v143, v1
	v_mov_b32_e32 v78, v86
	v_mov_b32_e32 v79, v90
	s_waitcnt vmcnt(0)
	v_mov_b64_e32 v[82:83], v[208:209]
	v_mov_b64_e32 v[84:85], v[210:211]
	v_mov_b64_e32 v[96:97], v[212:213]
	v_mov_b64_e32 v[98:99], v[214:215]
	v_mov_b64_e32 v[102:103], v[216:217]
	v_mov_b64_e32 v[104:105], v[218:219]
	v_mov_b64_e32 v[74:75], v[220:221]
	v_mov_b64_e32 v[76:77], v[222:223]
	v_pk_mul_f32 v[78:79], v[78:79], v[74:75]
	s_nop 0
	v_sub_f32_e32 v0, v78, v79
	v_mov_b32_e32 v78, v90
	v_mov_b32_e32 v79, v86
	v_pk_mul_f32 v[74:75], v[78:79], v[74:75]
	s_nop 0
	v_add_f32_e32 v75, v75, v74
	v_cndmask_b32_e64 v74, v86, v0, s[40:41]
	v_cndmask_b32_e64 v78, v90, v75, s[40:41]
	v_mov_b32_e32 v90, v87
	v_mov_b32_e32 v86, v91
	v_pk_mul_f32 v[80:81], v[90:91], v[76:77]
	v_pk_mul_f32 v[76:77], v[86:87], v[76:77]
	v_sub_f32_e32 v0, v80, v81
	v_add_f32_e32 v76, v77, v76
	v_cndmask_b32_e64 v79, v91, v76, s[40:41]
	v_mov_b32_e32 v76, v88
	v_mov_b32_e32 v77, v92
	v_pk_mul_f32 v[76:77], v[76:77], v[102:103]
	v_cndmask_b32_e64 v75, v87, v0, s[40:41]
	v_sub_f32_e32 v0, v76, v77
	v_mov_b32_e32 v76, v92
	v_mov_b32_e32 v77, v88
	v_pk_mul_f32 v[76:77], v[76:77], v[102:103]
	s_nop 0
	v_add_f32_e32 v77, v77, v76
	v_cndmask_b32_e64 v80, v92, v77, s[40:41]
	v_mov_b32_e32 v92, v89
	v_cndmask_b32_e64 v76, v88, v0, s[40:41]
	v_pk_mul_f32 v[86:87], v[92:93], v[104:105]
	v_mov_b32_e32 v88, v93
	v_sub_f32_e32 v0, v86, v87
	v_pk_mul_f32 v[86:87], v[88:89], v[104:105]
	v_cndmask_b32_e64 v77, v89, v0, s[40:41]
	v_add_f32_e32 v81, v87, v86
	v_mov_b32_e32 v86, v70
	v_mov_b32_e32 v87, v66
	v_pk_mul_f32 v[86:87], v[86:87], v[96:97]
	v_cndmask_b32_e64 v81, v93, v81, s[40:41]
	v_sub_f32_e32 v0, v86, v87
	v_mov_b32_e32 v86, v66
	v_mov_b32_e32 v87, v70
	v_pk_mul_f32 v[86:87], v[86:87], v[96:97]
	s_nop 0
	v_add_f32_e32 v87, v87, v86
	v_cndmask_b32_e64 v90, v66, v87, s[40:41]
	v_mov_b32_e32 v66, v71
	v_cndmask_b32_e64 v86, v70, v0, s[40:41]
	v_pk_mul_f32 v[88:89], v[66:67], v[98:99]
	v_mov_b32_e32 v70, v67
	v_sub_f32_e32 v0, v88, v89
	v_pk_mul_f32 v[88:89], v[70:71], v[98:99]
	v_cndmask_b32_e64 v87, v71, v0, s[40:41]
	v_add_f32_e32 v66, v89, v88
	v_cndmask_b32_e64 v91, v67, v66, s[40:41]
	v_mov_b32_e32 v66, v72
	v_mov_b32_e32 v67, v68
	v_pk_mul_f32 v[66:67], v[66:67], v[82:83]
	s_nop 0
	v_sub_f32_e32 v0, v66, v67
	v_mov_b32_e32 v66, v68
	v_mov_b32_e32 v67, v72
	v_pk_mul_f32 v[66:67], v[66:67], v[82:83]
	v_cndmask_b32_e64 v88, v72, v0, s[40:41]
	v_add_f32_e32 v66, v67, v66
	v_cndmask_b32_e64 v92, v68, v66, s[40:41]
	v_mov_b32_e32 v68, v73
	v_pk_mul_f32 v[66:67], v[68:69], v[84:85]
	v_mov_b32_e32 v72, v69
	v_sub_f32_e32 v0, v66, v67
	v_pk_mul_f32 v[66:67], v[72:73], v[84:85]
	v_cndmask_b32_e64 v89, v73, v0, s[40:41]
	v_add_f32_e32 v66, v67, v66
	v_cndmask_b32_e64 v93, v69, v66, s[40:41]
	v_mov_b64_e32 v[66:67], v[90:91]
	v_mov_b64_e32 v[70:71], v[86:87]
	v_mov_b64_e32 v[68:69], v[92:93]
	v_mov_b64_e32 v[72:73], v[88:89]
	v_mov_b64_e32 v[92:93], v[80:81]
	v_mov_b64_e32 v[88:89], v[76:77]
	v_mov_b64_e32 v[90:91], v[78:79]
	v_mov_b64_e32 v[86:87], v[74:75]
.LBB0_550:
	v_mul_u32_u24_e32 v0, 0x700, v100
	v_lshlrev_b32_e32 v0, 1, v0
	v_lshl_add_u64 v[74:75], s[64:65], 0, v[0:1]
	v_lshl_add_u64 v[74:75], s[88:89], 1, v[74:75]
	v_add_u32_e32 v82, 0x80, v176
	v_and_b32_e32 v227, 63, v186
	v_bfe_u32 v224, v82, 6, 5
	v_and_b32_e32 v228, 0x7ff, v82
	v_cndmask_b32_e64 v224, v227, v224, s[44:45]
	v_cndmask_b32_e64 v228, v224, v228, s[42:43]
	v_lshlrev_b32_e32 v228, 7, v228
	v_mov_b32_e32 v229, v1
	v_lshl_add_u64 v[224:225], s[36:37], 0, v[228:229]
	v_mov_b32_e32 v230, v142
	v_mov_b32_e32 v231, v1
	v_lshl_add_u64 v[224:225], v[224:225], 0, v[230:231]
	global_load_dwordx4 v[208:211], v[224:225], off offset:48
	global_load_dwordx4 v[212:215], v[224:225], off offset:32
	global_load_dwordx4 v[216:219], v[224:225], off offset:16
	global_load_dwordx4 v[220:223], v[224:225], off
	v_lshl_add_u64 v[78:79], v[158:159], 1, v[74:75]
	v_cvt_pk_bf16_f32 v74, v86, v87
	v_cvt_pk_bf16_f32 v75, v88, v89
	v_cvt_pk_bf16_f32 v76, v70, v71
	v_cvt_pk_bf16_f32 v77, v72, v73
	v_cvt_pk_bf16_f32 v70, v90, v91
	v_cvt_pk_bf16_f32 v71, v92, v93
	v_cvt_pk_bf16_f32 v72, v66, v67
	v_cvt_pk_bf16_f32 v73, v68, v69
	v_and_b32_e32 v84, 0xff, v82
	global_store_dwordx4 v[78:79], v[74:77], off
	global_store_dwordx4 v[78:79], v[70:73], off offset:32
	v_lshl_add_u32 v0, v84, 2, 0
	v_add_u32_e32 v0, 0x20400, v0
	ds_read_b32 v0, v0
	s_cmp_lt_i32 s78, 20
	s_cbranch_scc1 .LBB0_553
	s_mov_b64 s[94:95], -1
	s_mov_b64 s[84:85], 0
	s_cmp_gt_i32 s78, 25
	s_mov_b64 s[86:87], 0
	s_cbranch_scc0 .LBB0_554
	s_cmp_eq_u32 s78, 26
	s_mov_b64 s[94:95], 0
	s_cselect_b64 s[86:87], -1, 0
	s_branch .LBB0_554

.LBB0_567:
	s_and_b64 vcc, exec, s[86:87]
	s_cbranch_vccz .LBB0_569
	v_mov_b32_e32 v143, v1
	v_mov_b32_e32 v62, v70
	v_mov_b32_e32 v63, v74
	s_waitcnt vmcnt(0)
	v_mov_b64_e32 v[66:67], v[208:209]
	v_mov_b64_e32 v[68:69], v[210:211]
	v_mov_b64_e32 v[78:79], v[212:213]
	v_mov_b64_e32 v[80:81], v[214:215]
	v_mov_b64_e32 v[86:87], v[216:217]
	v_mov_b64_e32 v[88:89], v[218:219]
	v_mov_b64_e32 v[58:59], v[220:221]
	v_mov_b64_e32 v[60:61], v[222:223]
	v_pk_mul_f32 v[62:63], v[62:63], v[58:59]
	s_nop 0
	v_sub_f32_e32 v0, v62, v63
	v_mov_b32_e32 v62, v74
	v_mov_b32_e32 v63, v70
	v_pk_mul_f32 v[58:59], v[62:63], v[58:59]
	s_nop 0
	v_add_f32_e32 v59, v59, v58
	v_cndmask_b32_e64 v58, v70, v0, s[40:41]
	v_cndmask_b32_e64 v62, v74, v59, s[40:41]
	v_mov_b32_e32 v74, v71
	v_mov_b32_e32 v70, v75
	v_pk_mul_f32 v[64:65], v[74:75], v[60:61]
	v_pk_mul_f32 v[60:61], v[70:71], v[60:61]
	v_sub_f32_e32 v0, v64, v65
	v_add_f32_e32 v60, v61, v60
	v_cndmask_b32_e64 v63, v75, v60, s[40:41]
	v_mov_b32_e32 v60, v72
	v_mov_b32_e32 v61, v76
	v_pk_mul_f32 v[60:61], v[60:61], v[86:87]
	v_cndmask_b32_e64 v59, v71, v0, s[40:41]
	v_sub_f32_e32 v0, v60, v61
	v_mov_b32_e32 v60, v76
	v_mov_b32_e32 v61, v72
	v_pk_mul_f32 v[60:61], v[60:61], v[86:87]
	s_nop 0
	v_add_f32_e32 v61, v61, v60
	v_cndmask_b32_e64 v64, v76, v61, s[40:41]
	v_mov_b32_e32 v76, v73
	v_cndmask_b32_e64 v60, v72, v0, s[40:41]
	v_pk_mul_f32 v[70:71], v[76:77], v[88:89]
	v_mov_b32_e32 v72, v77
	v_sub_f32_e32 v0, v70, v71
	v_pk_mul_f32 v[70:71], v[72:73], v[88:89]
	v_cndmask_b32_e64 v61, v73, v0, s[40:41]
	v_add_f32_e32 v65, v71, v70
	v_mov_b32_e32 v70, v54
	v_mov_b32_e32 v71, v50
	v_pk_mul_f32 v[70:71], v[70:71], v[78:79]
	v_cndmask_b32_e64 v65, v77, v65, s[40:41]
	v_sub_f32_e32 v0, v70, v71
	v_mov_b32_e32 v70, v50
	v_mov_b32_e32 v71, v54
	v_pk_mul_f32 v[70:71], v[70:71], v[78:79]
	s_nop 0
	v_add_f32_e32 v71, v71, v70
	v_cndmask_b32_e64 v74, v50, v71, s[40:41]
	v_mov_b32_e32 v50, v55
	v_cndmask_b32_e64 v70, v54, v0, s[40:41]
	v_pk_mul_f32 v[72:73], v[50:51], v[80:81]
	v_mov_b32_e32 v54, v51
	v_sub_f32_e32 v0, v72, v73
	v_pk_mul_f32 v[72:73], v[54:55], v[80:81]
	v_cndmask_b32_e64 v71, v55, v0, s[40:41]
	v_add_f32_e32 v50, v73, v72
	v_cndmask_b32_e64 v75, v51, v50, s[40:41]
	v_mov_b32_e32 v50, v56
	v_mov_b32_e32 v51, v52
	v_pk_mul_f32 v[50:51], v[50:51], v[66:67]
	s_nop 0
	v_sub_f32_e32 v0, v50, v51
	v_mov_b32_e32 v50, v52
	v_mov_b32_e32 v51, v56
	v_pk_mul_f32 v[50:51], v[50:51], v[66:67]
	v_cndmask_b32_e64 v72, v56, v0, s[40:41]
	v_add_f32_e32 v50, v51, v50
	v_cndmask_b32_e64 v76, v52, v50, s[40:41]
	v_mov_b32_e32 v52, v57
	v_pk_mul_f32 v[50:51], v[52:53], v[68:69]
	v_mov_b32_e32 v56, v53
	v_sub_f32_e32 v0, v50, v51
	v_pk_mul_f32 v[50:51], v[56:57], v[68:69]
	v_cndmask_b32_e64 v73, v57, v0, s[40:41]
	v_add_f32_e32 v50, v51, v50
	v_cndmask_b32_e64 v77, v53, v50, s[40:41]
	v_mov_b64_e32 v[50:51], v[74:75]
	v_mov_b64_e32 v[54:55], v[70:71]
	v_mov_b64_e32 v[52:53], v[76:77]
	v_mov_b64_e32 v[56:57], v[72:73]
	v_mov_b64_e32 v[76:77], v[64:65]
	v_mov_b64_e32 v[72:73], v[60:61]
	v_mov_b64_e32 v[74:75], v[62:63]
	v_mov_b64_e32 v[70:71], v[58:59]
.LBB0_569:
	v_mul_u32_u24_e32 v0, 0x700, v84
	v_lshlrev_b32_e32 v0, 1, v0
	v_lshl_add_u64 v[58:59], s[64:65], 0, v[0:1]
	v_lshl_add_u64 v[58:59], s[88:89], 1, v[58:59]
	v_add_u32_e32 v66, 0x90, v176
	v_add_u32_e32 v226, 16, v186
	v_and_b32_e32 v227, 63, v226
	v_bfe_u32 v224, v66, 6, 5
	v_and_b32_e32 v228, 0x7ff, v66
	v_cndmask_b32_e64 v224, v227, v224, s[44:45]
	v_cndmask_b32_e64 v228, v224, v228, s[42:43]
	v_lshlrev_b32_e32 v228, 7, v228
	v_mov_b32_e32 v229, v1
	v_lshl_add_u64 v[224:225], s[36:37], 0, v[228:229]
	v_mov_b32_e32 v230, v142
	v_mov_b32_e32 v231, v1
	v_lshl_add_u64 v[224:225], v[224:225], 0, v[230:231]
	global_load_dwordx4 v[208:211], v[224:225], off offset:48
	global_load_dwordx4 v[212:215], v[224:225], off offset:32
	global_load_dwordx4 v[216:219], v[224:225], off offset:16
	global_load_dwordx4 v[220:223], v[224:225], off
	v_lshl_add_u64 v[62:63], v[158:159], 1, v[58:59]
	v_cvt_pk_bf16_f32 v58, v70, v71
	v_cvt_pk_bf16_f32 v59, v72, v73
	v_cvt_pk_bf16_f32 v60, v54, v55
	v_cvt_pk_bf16_f32 v61, v56, v57
	v_cvt_pk_bf16_f32 v54, v74, v75
	v_cvt_pk_bf16_f32 v55, v76, v77
	v_cvt_pk_bf16_f32 v56, v50, v51
	v_cvt_pk_bf16_f32 v57, v52, v53
	v_and_b32_e32 v68, 0xff, v66
	global_store_dwordx4 v[62:63], v[58:61], off
	global_store_dwordx4 v[62:63], v[54:57], off offset:32
	v_lshl_add_u32 v0, v68, 2, 0
	v_add_u32_e32 v0, 0x20400, v0
	ds_read_b32 v0, v0
	s_cmp_lt_i32 s78, 20
	s_cbranch_scc1 .LBB0_572
	s_mov_b64 s[94:95], -1
	s_mov_b64 s[84:85], 0
	s_cmp_gt_i32 s78, 25
	s_mov_b64 s[86:87], 0
	s_cbranch_scc0 .LBB0_573
	s_cmp_eq_u32 s78, 26
	s_mov_b64 s[94:95], 0
	s_cselect_b64 s[86:87], -1, 0
	s_branch .LBB0_573

.LBB0_586:
	s_and_b64 vcc, exec, s[86:87]
	s_cbranch_vccz .LBB0_588
	v_mov_b32_e32 v143, v1
	v_mov_b32_e32 v46, v54
	v_mov_b32_e32 v47, v58
	s_waitcnt vmcnt(0)
	v_mov_b64_e32 v[50:51], v[208:209]
	v_mov_b64_e32 v[52:53], v[210:211]
	v_mov_b64_e32 v[62:63], v[212:213]
	v_mov_b64_e32 v[64:65], v[214:215]
	v_mov_b64_e32 v[70:71], v[216:217]
	v_mov_b64_e32 v[72:73], v[218:219]
	v_mov_b64_e32 v[42:43], v[220:221]
	v_mov_b64_e32 v[44:45], v[222:223]
	v_pk_mul_f32 v[46:47], v[46:47], v[42:43]
	s_nop 0
	v_sub_f32_e32 v0, v46, v47
	v_mov_b32_e32 v46, v58
	v_mov_b32_e32 v47, v54
	v_pk_mul_f32 v[42:43], v[46:47], v[42:43]
	s_nop 0
	v_add_f32_e32 v43, v43, v42
	v_cndmask_b32_e64 v42, v54, v0, s[40:41]
	v_cndmask_b32_e64 v46, v58, v43, s[40:41]
	v_mov_b32_e32 v58, v55
	v_mov_b32_e32 v54, v59
	v_pk_mul_f32 v[48:49], v[58:59], v[44:45]
	v_pk_mul_f32 v[44:45], v[54:55], v[44:45]
	v_sub_f32_e32 v0, v48, v49
	v_add_f32_e32 v44, v45, v44
	v_cndmask_b32_e64 v47, v59, v44, s[40:41]
	v_mov_b32_e32 v44, v56
	v_mov_b32_e32 v45, v60
	v_pk_mul_f32 v[44:45], v[44:45], v[70:71]
	v_cndmask_b32_e64 v43, v55, v0, s[40:41]
	v_sub_f32_e32 v0, v44, v45
	v_mov_b32_e32 v44, v60
	v_mov_b32_e32 v45, v56
	v_pk_mul_f32 v[44:45], v[44:45], v[70:71]
	s_nop 0
	v_add_f32_e32 v45, v45, v44
	v_cndmask_b32_e64 v48, v60, v45, s[40:41]
	v_mov_b32_e32 v60, v57
	v_cndmask_b32_e64 v44, v56, v0, s[40:41]
	v_pk_mul_f32 v[54:55], v[60:61], v[72:73]
	v_mov_b32_e32 v56, v61
	v_sub_f32_e32 v0, v54, v55
	v_pk_mul_f32 v[54:55], v[56:57], v[72:73]
	v_cndmask_b32_e64 v45, v57, v0, s[40:41]
	v_add_f32_e32 v49, v55, v54
	v_mov_b32_e32 v54, v38
	v_mov_b32_e32 v55, v34
	v_pk_mul_f32 v[54:55], v[54:55], v[62:63]
	v_cndmask_b32_e64 v49, v61, v49, s[40:41]
	v_sub_f32_e32 v0, v54, v55
	v_mov_b32_e32 v54, v34
	v_mov_b32_e32 v55, v38
	v_pk_mul_f32 v[54:55], v[54:55], v[62:63]
	s_nop 0
	v_add_f32_e32 v55, v55, v54
	v_cndmask_b32_e64 v58, v34, v55, s[40:41]
	v_mov_b32_e32 v34, v39
	v_cndmask_b32_e64 v54, v38, v0, s[40:41]
	v_pk_mul_f32 v[56:57], v[34:35], v[64:65]
	v_mov_b32_e32 v38, v35
	v_sub_f32_e32 v0, v56, v57
	v_pk_mul_f32 v[56:57], v[38:39], v[64:65]
	v_cndmask_b32_e64 v55, v39, v0, s[40:41]
	v_add_f32_e32 v34, v57, v56
	v_cndmask_b32_e64 v59, v35, v34, s[40:41]
	v_mov_b32_e32 v34, v40
	v_mov_b32_e32 v35, v36
	v_pk_mul_f32 v[34:35], v[34:35], v[50:51]
	s_nop 0
	v_sub_f32_e32 v0, v34, v35
	v_mov_b32_e32 v34, v36
	v_mov_b32_e32 v35, v40
	v_pk_mul_f32 v[34:35], v[34:35], v[50:51]
	v_cndmask_b32_e64 v56, v40, v0, s[40:41]
	v_add_f32_e32 v34, v35, v34
	v_cndmask_b32_e64 v60, v36, v34, s[40:41]
	v_mov_b32_e32 v36, v41
	v_pk_mul_f32 v[34:35], v[36:37], v[52:53]
	v_mov_b32_e32 v40, v37
	v_sub_f32_e32 v0, v34, v35
	v_pk_mul_f32 v[34:35], v[40:41], v[52:53]
	v_cndmask_b32_e64 v57, v41, v0, s[40:41]
	v_add_f32_e32 v34, v35, v34
	v_cndmask_b32_e64 v61, v37, v34, s[40:41]
	v_mov_b64_e32 v[34:35], v[58:59]
	v_mov_b64_e32 v[38:39], v[54:55]
	v_mov_b64_e32 v[36:37], v[60:61]
	v_mov_b64_e32 v[40:41], v[56:57]
	v_mov_b64_e32 v[60:61], v[48:49]
	v_mov_b64_e32 v[56:57], v[44:45]
	v_mov_b64_e32 v[58:59], v[46:47]
	v_mov_b64_e32 v[54:55], v[42:43]
.LBB0_588:
	v_mul_u32_u24_e32 v0, 0x700, v68
	v_lshlrev_b32_e32 v0, 1, v0
	v_lshl_add_u64 v[42:43], s[64:65], 0, v[0:1]
	v_lshl_add_u64 v[42:43], s[88:89], 1, v[42:43]
	v_add_u32_e32 v50, 0xa0, v176
	v_add_u32_e32 v226, 32, v186
	v_and_b32_e32 v227, 63, v226
	v_bfe_u32 v224, v50, 6, 5
	v_and_b32_e32 v228, 0x7ff, v50
	v_cndmask_b32_e64 v224, v227, v224, s[44:45]
	v_cndmask_b32_e64 v228, v224, v228, s[42:43]
	v_lshlrev_b32_e32 v228, 7, v228
	v_mov_b32_e32 v229, v1
	v_lshl_add_u64 v[224:225], s[36:37], 0, v[228:229]
	v_mov_b32_e32 v230, v142
	v_mov_b32_e32 v231, v1
	v_lshl_add_u64 v[224:225], v[224:225], 0, v[230:231]
	global_load_dwordx4 v[208:211], v[224:225], off offset:48
	global_load_dwordx4 v[212:215], v[224:225], off offset:32
	global_load_dwordx4 v[216:219], v[224:225], off offset:16
	global_load_dwordx4 v[220:223], v[224:225], off
	v_lshl_add_u64 v[46:47], v[158:159], 1, v[42:43]
	v_cvt_pk_bf16_f32 v42, v54, v55
	v_cvt_pk_bf16_f32 v43, v56, v57
	v_cvt_pk_bf16_f32 v44, v38, v39
	v_cvt_pk_bf16_f32 v45, v40, v41
	v_cvt_pk_bf16_f32 v38, v58, v59
	v_cvt_pk_bf16_f32 v39, v60, v61
	v_cvt_pk_bf16_f32 v40, v34, v35
	v_cvt_pk_bf16_f32 v41, v36, v37
	v_and_b32_e32 v52, 0xff, v50
	global_store_dwordx4 v[46:47], v[42:45], off
	global_store_dwordx4 v[46:47], v[38:41], off offset:32
	v_lshl_add_u32 v0, v52, 2, 0
	v_add_u32_e32 v0, 0x20400, v0
	ds_read_b32 v0, v0
	s_cmp_lt_i32 s78, 20
	s_cbranch_scc1 .LBB0_591
	s_mov_b64 s[94:95], -1
	s_mov_b64 s[84:85], 0
	s_cmp_gt_i32 s78, 25
	s_mov_b64 s[86:87], 0
	s_cbranch_scc0 .LBB0_592
	s_cmp_eq_u32 s78, 26
	s_mov_b64 s[94:95], 0
	s_cselect_b64 s[86:87], -1, 0
	s_branch .LBB0_592

.LBB0_605:
	s_and_b64 vcc, exec, s[86:87]
	s_cbranch_vccz .LBB0_607
	v_mov_b32_e32 v143, v1
	v_mov_b32_e32 v30, v38
	v_mov_b32_e32 v31, v42
	s_waitcnt vmcnt(0)
	v_mov_b64_e32 v[34:35], v[208:209]
	v_mov_b64_e32 v[36:37], v[210:211]
	v_mov_b64_e32 v[46:47], v[212:213]
	v_mov_b64_e32 v[48:49], v[214:215]
	v_mov_b64_e32 v[54:55], v[216:217]
	v_mov_b64_e32 v[56:57], v[218:219]
	v_mov_b64_e32 v[26:27], v[220:221]
	v_mov_b64_e32 v[28:29], v[222:223]
	v_pk_mul_f32 v[30:31], v[30:31], v[26:27]
	s_nop 0
	v_sub_f32_e32 v0, v30, v31
	v_mov_b32_e32 v30, v42
	v_mov_b32_e32 v31, v38
	v_pk_mul_f32 v[26:27], v[30:31], v[26:27]
	s_nop 0
	v_add_f32_e32 v27, v27, v26
	v_cndmask_b32_e64 v26, v38, v0, s[40:41]
	v_cndmask_b32_e64 v30, v42, v27, s[40:41]
	v_mov_b32_e32 v42, v39
	v_mov_b32_e32 v38, v43
	v_pk_mul_f32 v[32:33], v[42:43], v[28:29]
	v_pk_mul_f32 v[28:29], v[38:39], v[28:29]
	v_sub_f32_e32 v0, v32, v33
	v_add_f32_e32 v28, v29, v28
	v_cndmask_b32_e64 v31, v43, v28, s[40:41]
	v_mov_b32_e32 v28, v40
	v_mov_b32_e32 v29, v44
	v_pk_mul_f32 v[28:29], v[28:29], v[54:55]
	v_cndmask_b32_e64 v27, v39, v0, s[40:41]
	v_sub_f32_e32 v0, v28, v29
	v_mov_b32_e32 v28, v44
	v_mov_b32_e32 v29, v40
	v_pk_mul_f32 v[28:29], v[28:29], v[54:55]
	s_nop 0
	v_add_f32_e32 v29, v29, v28
	v_cndmask_b32_e64 v32, v44, v29, s[40:41]
	v_mov_b32_e32 v44, v41
	v_cndmask_b32_e64 v28, v40, v0, s[40:41]
	v_pk_mul_f32 v[38:39], v[44:45], v[56:57]
	v_mov_b32_e32 v40, v45
	v_sub_f32_e32 v0, v38, v39
	v_pk_mul_f32 v[38:39], v[40:41], v[56:57]
	v_cndmask_b32_e64 v29, v41, v0, s[40:41]
	v_add_f32_e32 v33, v39, v38
	v_mov_b32_e32 v38, v22
	v_mov_b32_e32 v39, v18
	v_pk_mul_f32 v[38:39], v[38:39], v[46:47]
	v_cndmask_b32_e64 v33, v45, v33, s[40:41]
	v_sub_f32_e32 v0, v38, v39
	v_mov_b32_e32 v38, v18
	v_mov_b32_e32 v39, v22
	v_pk_mul_f32 v[38:39], v[38:39], v[46:47]
	s_nop 0
	v_add_f32_e32 v39, v39, v38
	v_cndmask_b32_e64 v42, v18, v39, s[40:41]
	v_mov_b32_e32 v18, v23
	v_cndmask_b32_e64 v38, v22, v0, s[40:41]
	v_pk_mul_f32 v[40:41], v[18:19], v[48:49]
	v_mov_b32_e32 v22, v19
	v_sub_f32_e32 v0, v40, v41
	v_pk_mul_f32 v[40:41], v[22:23], v[48:49]
	v_cndmask_b32_e64 v39, v23, v0, s[40:41]
	v_add_f32_e32 v18, v41, v40
	v_cndmask_b32_e64 v43, v19, v18, s[40:41]
	v_mov_b32_e32 v18, v24
	v_mov_b32_e32 v19, v20
	v_pk_mul_f32 v[18:19], v[18:19], v[34:35]
	s_nop 0
	v_sub_f32_e32 v0, v18, v19
	v_mov_b32_e32 v18, v20
	v_mov_b32_e32 v19, v24
	v_pk_mul_f32 v[18:19], v[18:19], v[34:35]
	v_cndmask_b32_e64 v40, v24, v0, s[40:41]
	v_add_f32_e32 v18, v19, v18
	v_cndmask_b32_e64 v44, v20, v18, s[40:41]
	v_mov_b32_e32 v20, v25
	v_pk_mul_f32 v[18:19], v[20:21], v[36:37]
	v_mov_b32_e32 v24, v21
	v_sub_f32_e32 v0, v18, v19
	v_pk_mul_f32 v[18:19], v[24:25], v[36:37]
	v_cndmask_b32_e64 v41, v25, v0, s[40:41]
	v_add_f32_e32 v18, v19, v18
	v_cndmask_b32_e64 v45, v21, v18, s[40:41]
	v_mov_b64_e32 v[18:19], v[42:43]
	v_mov_b64_e32 v[22:23], v[38:39]
	v_mov_b64_e32 v[20:21], v[44:45]
	v_mov_b64_e32 v[24:25], v[40:41]
	v_mov_b64_e32 v[44:45], v[32:33]
	v_mov_b64_e32 v[40:41], v[28:29]
	v_mov_b64_e32 v[42:43], v[30:31]
	v_mov_b64_e32 v[38:39], v[26:27]
.LBB0_607:
	v_mul_u32_u24_e32 v0, 0x700, v52
	v_lshlrev_b32_e32 v0, 1, v0
	v_lshl_add_u64 v[26:27], s[64:65], 0, v[0:1]
	v_lshl_add_u64 v[26:27], s[88:89], 1, v[26:27]
	v_add_u32_e32 v34, 0xb0, v176
	v_add_u32_e32 v226, 48, v186
	v_and_b32_e32 v227, 63, v226
	v_bfe_u32 v224, v34, 6, 5
	v_and_b32_e32 v228, 0x7ff, v34
	v_cndmask_b32_e64 v224, v227, v224, s[44:45]
	v_cndmask_b32_e64 v228, v224, v228, s[42:43]
	v_lshlrev_b32_e32 v228, 7, v228
	v_mov_b32_e32 v229, v1
	v_lshl_add_u64 v[224:225], s[36:37], 0, v[228:229]
	v_mov_b32_e32 v230, v142
	v_mov_b32_e32 v231, v1
	v_lshl_add_u64 v[224:225], v[224:225], 0, v[230:231]
	global_load_dwordx4 v[208:211], v[224:225], off offset:48
	global_load_dwordx4 v[212:215], v[224:225], off offset:32
	global_load_dwordx4 v[216:219], v[224:225], off offset:16
	global_load_dwordx4 v[220:223], v[224:225], off
	v_lshl_add_u64 v[30:31], v[158:159], 1, v[26:27]
	v_cvt_pk_bf16_f32 v26, v38, v39
	v_cvt_pk_bf16_f32 v27, v40, v41
	v_cvt_pk_bf16_f32 v28, v22, v23
	v_cvt_pk_bf16_f32 v29, v24, v25
	v_cvt_pk_bf16_f32 v22, v42, v43
	v_cvt_pk_bf16_f32 v23, v44, v45
	v_cvt_pk_bf16_f32 v24, v18, v19
	v_cvt_pk_bf16_f32 v25, v20, v21
	v_and_b32_e32 v36, 0xff, v34
	global_store_dwordx4 v[30:31], v[26:29], off
	global_store_dwordx4 v[30:31], v[22:25], off offset:32
	v_lshl_add_u32 v0, v36, 2, 0
	v_add_u32_e32 v0, 0x20400, v0
	ds_read_b32 v0, v0
	s_cmp_lt_i32 s78, 20
	s_cbranch_scc1 .LBB0_610
	s_mov_b64 s[94:95], -1
	s_mov_b64 s[84:85], 0
	s_cmp_gt_i32 s78, 25
	s_mov_b64 s[86:87], 0
	s_cbranch_scc0 .LBB0_611
	s_cmp_eq_u32 s78, 26
	s_mov_b64 s[94:95], 0
	s_cselect_b64 s[86:87], -1, 0
	s_branch .LBB0_611

.LBB0_625:
	v_mov_b32_e32 v143, v1
	v_mov_b32_e32 v14, v22
	v_mov_b32_e32 v15, v26
	s_waitcnt vmcnt(0)
	v_mov_b64_e32 v[18:19], v[208:209]
	v_mov_b64_e32 v[20:21], v[210:211]
	v_mov_b64_e32 v[30:31], v[212:213]
	v_mov_b64_e32 v[32:33], v[214:215]
	v_mov_b64_e32 v[38:39], v[216:217]
	v_mov_b64_e32 v[40:41], v[218:219]
	v_mov_b64_e32 v[10:11], v[220:221]
	v_mov_b64_e32 v[12:13], v[222:223]
	v_pk_mul_f32 v[14:15], v[14:15], v[10:11]
	s_nop 0
	v_sub_f32_e32 v0, v14, v15
	v_mov_b32_e32 v14, v26
	v_mov_b32_e32 v15, v22
	v_pk_mul_f32 v[10:11], v[14:15], v[10:11]
	s_nop 0
	v_add_f32_e32 v11, v11, v10
	v_cndmask_b32_e64 v10, v22, v0, s[40:41]
	v_cndmask_b32_e64 v14, v26, v11, s[40:41]
	v_mov_b32_e32 v26, v23
	v_mov_b32_e32 v22, v27
	v_pk_mul_f32 v[16:17], v[26:27], v[12:13]
	v_pk_mul_f32 v[12:13], v[22:23], v[12:13]
	v_sub_f32_e32 v0, v16, v17
	v_add_f32_e32 v12, v13, v12
	v_cndmask_b32_e64 v15, v27, v12, s[40:41]
	v_mov_b32_e32 v12, v24
	v_mov_b32_e32 v13, v28
	v_pk_mul_f32 v[12:13], v[12:13], v[38:39]
	v_cndmask_b32_e64 v11, v23, v0, s[40:41]
	v_sub_f32_e32 v0, v12, v13
	v_mov_b32_e32 v12, v28
	v_mov_b32_e32 v13, v24
	v_pk_mul_f32 v[12:13], v[12:13], v[38:39]
	s_nop 0
	v_add_f32_e32 v13, v13, v12
	v_cndmask_b32_e64 v16, v28, v13, s[40:41]
	v_mov_b32_e32 v28, v25
	v_cndmask_b32_e64 v12, v24, v0, s[40:41]
	v_pk_mul_f32 v[22:23], v[28:29], v[40:41]
	v_mov_b32_e32 v24, v29
	v_sub_f32_e32 v0, v22, v23
	v_pk_mul_f32 v[22:23], v[24:25], v[40:41]
	v_cndmask_b32_e64 v13, v25, v0, s[40:41]
	v_add_f32_e32 v17, v23, v22
	v_mov_b32_e32 v22, v6
	v_mov_b32_e32 v23, v2
	v_pk_mul_f32 v[22:23], v[22:23], v[30:31]
	v_cndmask_b32_e64 v17, v29, v17, s[40:41]
	v_sub_f32_e32 v0, v22, v23
	v_mov_b32_e32 v22, v2
	v_mov_b32_e32 v23, v6
	v_pk_mul_f32 v[22:23], v[22:23], v[30:31]
	s_nop 0
	v_add_f32_e32 v23, v23, v22
	v_cndmask_b32_e64 v26, v2, v23, s[40:41]
	v_mov_b32_e32 v2, v7
	v_cndmask_b32_e64 v22, v6, v0, s[40:41]
	v_pk_mul_f32 v[24:25], v[2:3], v[32:33]
	v_mov_b32_e32 v6, v3
	v_sub_f32_e32 v0, v24, v25
	v_pk_mul_f32 v[24:25], v[6:7], v[32:33]
	v_cndmask_b32_e64 v23, v7, v0, s[40:41]
	v_add_f32_e32 v2, v25, v24
	v_cndmask_b32_e64 v27, v3, v2, s[40:41]
	v_mov_b32_e32 v2, v8
	v_mov_b32_e32 v3, v4
	v_pk_mul_f32 v[2:3], v[2:3], v[18:19]
	s_nop 0
	v_sub_f32_e32 v0, v2, v3
	v_mov_b32_e32 v2, v4
	v_mov_b32_e32 v3, v8
	v_pk_mul_f32 v[2:3], v[2:3], v[18:19]
	v_cndmask_b32_e64 v24, v8, v0, s[40:41]
	v_add_f32_e32 v2, v3, v2
	v_cndmask_b32_e64 v28, v4, v2, s[40:41]
	v_mov_b32_e32 v4, v9
	v_pk_mul_f32 v[2:3], v[4:5], v[20:21]
	v_mov_b32_e32 v8, v5
	v_sub_f32_e32 v0, v2, v3
	v_pk_mul_f32 v[2:3], v[8:9], v[20:21]
	v_cndmask_b32_e64 v25, v9, v0, s[40:41]
	v_add_f32_e32 v2, v3, v2
	v_cndmask_b32_e64 v29, v5, v2, s[40:41]
	v_mov_b64_e32 v[2:3], v[26:27]
	v_mov_b64_e32 v[6:7], v[22:23]
	v_mov_b64_e32 v[4:5], v[28:29]
	v_mov_b64_e32 v[8:9], v[24:25]
	v_mov_b64_e32 v[28:29], v[16:17]
	v_mov_b64_e32 v[24:25], v[12:13]
	v_mov_b64_e32 v[26:27], v[14:15]
	v_mov_b64_e32 v[22:23], v[10:11]
